# combo2 with the barrier variant where every waiter/leader polls the top arrival counter directly (no generation words)
# speedup vs baseline: 1.0113x; 1.0015x over previous
.LBB0_89:
	s_or_b64 exec, exec, s[10:11]
	v_cvt_f32_u32_e32 v6, v4
	s_waitcnt vmcnt(0)
	v_readfirstlane_b32 s3, v5
	v_sub_u32_e32 v5, 0, v4
	v_rcp_iflag_f32_e32 v6, v6
	v_add_u32_e32 v7, s3, v3
	v_mul_f32_e32 v6, 0x4f7ffffe, v6
	v_cvt_u32_f32_e32 v6, v6
	v_mul_lo_u32 v3, v5, v6
	v_mul_hi_u32 v3, v6, v3
	v_add_u32_e32 v3, v6, v3
	v_mul_hi_u32 v3, v7, v3
	v_mul_lo_u32 v5, v3, v4
	v_sub_u32_e32 v5, v7, v5
	v_add_u32_e32 v6, 1, v3
	v_cmp_ge_u32_e32 vcc, v5, v4
	s_nop 1
	v_cndmask_b32_e32 v3, v3, v6, vcc
	v_sub_u32_e32 v6, v5, v4
	v_cndmask_b32_e32 v5, v5, v6, vcc
	v_add_u32_e32 v6, 1, v3
	v_cmp_ge_u32_e32 vcc, v5, v4
	v_add_u32_e32 v5, 1, v7
	s_nop 0
	v_cndmask_b32_e32 v3, v3, v6, vcc
	v_mul_lo_u32 v6, v4, v3
	v_add_u32_e32 v4, v6, v4
	v_cmp_ne_u32_e32 vcc, v5, v4
	s_and_saveexec_b64 s[8:9], vcc
	s_xor_b64 s[8:9], exec, s[8:9]
	s_cbranch_execz .LBB0_103
	s_waitcnt lgkmcnt(0)
	v_mov_b32_e32 v2, 0x24004
	ds_read_b32 v2, v2
	s_add_u32 s14, s68, 0x3400
	s_addc_u32 s15, s69, 0
	s_waitcnt lgkmcnt(0)
	v_mad_u32_u24 v3, v3, v2, v2
	v_mov_b32_e32 v2, 0
	global_load_dword v2, v2, s[14:15] sc1
	s_waitcnt vmcnt(0)
	v_cmp_lt_u32_e32 vcc, v2, v3
	s_and_saveexec_b64 s[10:11], vcc
	s_cbranch_execz .LBB0_102
	s_add_u32 s12, s96, 0xd3a0200
	s_addc_u32 s13, s97, 0
	s_mov_b32 s3, 1
	s_mov_b64 s[16:17], 0
	v_mov_b32_e32 v2, 0
	s_branch .LBB0_93

.LBB0_97:
	global_load_dword v4, v2, s[14:15] sc1
	s_add_i32 s3, s3, 1
	s_mov_b64 s[22:23], -1
	s_waitcnt vmcnt(0)
	v_cmp_ge_u32_e32 vcc, v4, v3
	s_orn2_b64 s[20:21], vcc, exec
	s_branch .LBB0_92

.LBB0_106:
	s_or_b64 exec, exec, s[10:11]
	v_cvt_f32_u32_e32 v5, v2
	s_waitcnt vmcnt(0)
	v_readfirstlane_b32 s3, v4
	s_add_u32 s10, s96, 0xd3a3400
	s_addc_u32 s11, s97, 0
	v_rcp_iflag_f32_e32 v5, v5
	v_add_u32_e32 v3, s3, v3
	v_add_u32_e32 v6, 1, v3
	s_mov_b64 s[12:13], -1
	v_mul_f32_e32 v4, 0x4f7ffffe, v5
	v_cvt_u32_f32_e32 v4, v4
	v_sub_u32_e32 v5, 0, v2
	v_mul_lo_u32 v5, v5, v4
	v_mul_hi_u32 v5, v4, v5
	v_add_u32_e32 v4, v4, v5
	v_mul_hi_u32 v4, v3, v4
	v_mul_lo_u32 v5, v4, v2
	v_sub_u32_e32 v3, v3, v5
	v_add_u32_e32 v7, 1, v4
	v_cmp_ge_u32_e32 vcc, v3, v2
	v_sub_u32_e32 v5, v3, v2
	s_nop 0
	v_cndmask_b32_e32 v4, v4, v7, vcc
	v_cndmask_b32_e32 v3, v3, v5, vcc
	v_add_u32_e32 v5, 1, v4
	v_cmp_ge_u32_e32 vcc, v3, v2
	s_nop 1
	v_cndmask_b32_e32 v4, v4, v5, vcc
	v_mul_lo_u32 v3, v2, v4
	v_add_u32_e32 v2, v3, v2
	v_mov_b32_e32 v4, v2
	v_cmp_ne_u32_e32 vcc, v6, v2
	v_mov_b64_e32 v[2:3], s[10:11]
	s_and_saveexec_b64 s[8:9], vcc
	s_cbranch_execz .LBB0_118
	v_mov_b32_e32 v2, 0
	global_load_dword v3, v2, s[10:11] sc1
	s_mov_b64 s[16:17], 0
	s_waitcnt vmcnt(0)
	v_cmp_lt_u32_e32 vcc, v3, v4
	s_and_saveexec_b64 s[14:15], vcc
	s_cbranch_execz .LBB0_117
	s_add_u32 s12, s96, 0xd3a0200
	s_addc_u32 s13, s97, 0
	s_mov_b32 s3, 1
	s_branch .LBB0_110

.LBB0_114:
	global_load_dword v3, v2, s[10:11] sc1
	s_add_i32 s3, s3, 1
	s_mov_b64 s[20:21], -1
	s_waitcnt vmcnt(0)
	v_cmp_ge_u32_e32 vcc, v3, v4
	s_orn2_b64 s[24:25], vcc, exec
	s_branch .LBB0_109

.LBB0_417:
	s_or_b64 exec, exec, s[8:9]
	v_cvt_f32_u32_e32 v6, v4
	s_waitcnt vmcnt(0)
	v_readfirstlane_b32 s3, v5
	v_sub_u32_e32 v5, 0, v4
	v_rcp_iflag_f32_e32 v6, v6
	v_add_u32_e32 v7, s3, v3
	v_mul_f32_e32 v6, 0x4f7ffffe, v6
	v_cvt_u32_f32_e32 v6, v6
	v_mul_lo_u32 v3, v5, v6
	v_mul_hi_u32 v3, v6, v3
	v_add_u32_e32 v3, v6, v3
	v_mul_hi_u32 v3, v7, v3
	v_mul_lo_u32 v5, v3, v4
	v_sub_u32_e32 v5, v7, v5
	v_add_u32_e32 v6, 1, v3
	v_cmp_ge_u32_e32 vcc, v5, v4
	s_nop 1
	v_cndmask_b32_e32 v3, v3, v6, vcc
	v_sub_u32_e32 v6, v5, v4
	v_cndmask_b32_e32 v5, v5, v6, vcc
	v_add_u32_e32 v6, 1, v3
	v_cmp_ge_u32_e32 vcc, v5, v4
	v_add_u32_e32 v5, 1, v7
	s_nop 0
	v_cndmask_b32_e32 v3, v3, v6, vcc
	v_mul_lo_u32 v6, v4, v3
	v_add_u32_e32 v4, v6, v4
	v_cmp_ne_u32_e32 vcc, v5, v4
	s_and_saveexec_b64 s[6:7], vcc
	s_xor_b64 s[6:7], exec, s[6:7]
	s_cbranch_execz .LBB0_431
	s_waitcnt lgkmcnt(0)
	v_mov_b32_e32 v2, 0x24004
	ds_read_b32 v2, v2
	s_add_u32 s12, s68, 0x3400
	s_addc_u32 s13, s69, 0
	s_waitcnt lgkmcnt(0)
	v_mad_u32_u24 v3, v3, v2, v2
	v_mov_b32_e32 v2, 0
	global_load_dword v2, v2, s[12:13] sc1
	s_waitcnt vmcnt(0)
	v_cmp_lt_u32_e32 vcc, v2, v3
	s_and_saveexec_b64 s[8:9], vcc
	s_cbranch_execz .LBB0_430
	s_add_u32 s10, s96, 0xd3a0200
	s_addc_u32 s11, s97, 0
	s_mov_b32 s3, 1
	s_mov_b64 s[14:15], 0
	v_mov_b32_e32 v2, 0
	s_branch .LBB0_421

.LBB0_425:
	global_load_dword v4, v2, s[12:13] sc1
	s_add_i32 s3, s3, 1
	s_mov_b64 s[20:21], -1
	s_waitcnt vmcnt(0)
	v_cmp_ge_u32_e32 vcc, v4, v3
	s_orn2_b64 s[18:19], vcc, exec
	s_branch .LBB0_420

.LBB0_434:
	s_or_b64 exec, exec, s[8:9]
	v_cvt_f32_u32_e32 v5, v2
	s_waitcnt vmcnt(0)
	v_readfirstlane_b32 s3, v4
	s_add_u32 s8, s96, 0xd3a3400
	s_addc_u32 s9, s97, 0
	v_rcp_iflag_f32_e32 v5, v5
	v_add_u32_e32 v3, s3, v3
	v_add_u32_e32 v6, 1, v3
	s_mov_b64 s[10:11], -1
	v_mul_f32_e32 v4, 0x4f7ffffe, v5
	v_cvt_u32_f32_e32 v4, v4
	v_sub_u32_e32 v5, 0, v2
	v_mul_lo_u32 v5, v5, v4
	v_mul_hi_u32 v5, v4, v5
	v_add_u32_e32 v4, v4, v5
	v_mul_hi_u32 v4, v3, v4
	v_mul_lo_u32 v5, v4, v2
	v_sub_u32_e32 v3, v3, v5
	v_add_u32_e32 v7, 1, v4
	v_cmp_ge_u32_e32 vcc, v3, v2
	v_sub_u32_e32 v5, v3, v2
	s_nop 0
	v_cndmask_b32_e32 v4, v4, v7, vcc
	v_cndmask_b32_e32 v3, v3, v5, vcc
	v_add_u32_e32 v5, 1, v4
	v_cmp_ge_u32_e32 vcc, v3, v2
	s_nop 1
	v_cndmask_b32_e32 v4, v4, v5, vcc
	v_mul_lo_u32 v3, v2, v4
	v_add_u32_e32 v2, v3, v2
	v_mov_b32_e32 v4, v2
	v_cmp_ne_u32_e32 vcc, v6, v2
	v_mov_b64_e32 v[2:3], s[8:9]
	s_and_saveexec_b64 s[6:7], vcc
	s_cbranch_execz .LBB0_446
	v_mov_b32_e32 v2, 0
	global_load_dword v3, v2, s[8:9] sc1
	s_mov_b64 s[14:15], 0
	s_waitcnt vmcnt(0)
	v_cmp_lt_u32_e32 vcc, v3, v4
	s_and_saveexec_b64 s[12:13], vcc
	s_cbranch_execz .LBB0_445
	s_add_u32 s10, s96, 0xd3a0200
	s_addc_u32 s11, s97, 0
	s_mov_b32 s3, 1
	s_branch .LBB0_438

.LBB0_442:
	global_load_dword v3, v2, s[8:9] sc1
	s_add_i32 s3, s3, 1
	s_mov_b64 s[18:19], -1
	s_waitcnt vmcnt(0)
	v_cmp_ge_u32_e32 vcc, v3, v4
	s_orn2_b64 s[22:23], vcc, exec
	s_branch .LBB0_437

.LBB0_588:
	s_or_b64 exec, exec, s[10:11]
	v_cvt_f32_u32_e32 v5, v3
	s_waitcnt vmcnt(0)
	v_readfirstlane_b32 s3, v4
	v_sub_u32_e32 v4, 0, v3
	v_rcp_iflag_f32_e32 v5, v5
	v_add_u32_e32 v6, s3, v2
	v_mul_f32_e32 v5, 0x4f7ffffe, v5
	v_cvt_u32_f32_e32 v5, v5
	v_mul_lo_u32 v2, v4, v5
	v_mul_hi_u32 v2, v5, v2
	v_add_u32_e32 v2, v5, v2
	v_mul_hi_u32 v2, v6, v2
	v_mul_lo_u32 v4, v2, v3
	v_sub_u32_e32 v4, v6, v4
	v_add_u32_e32 v5, 1, v2
	v_cmp_ge_u32_e32 vcc, v4, v3
	s_nop 1
	v_cndmask_b32_e32 v2, v2, v5, vcc
	v_sub_u32_e32 v5, v4, v3
	v_cndmask_b32_e32 v4, v4, v5, vcc
	v_add_u32_e32 v5, 1, v2
	v_cmp_ge_u32_e32 vcc, v4, v3
	v_add_u32_e32 v4, 1, v6
	s_nop 0
	v_cndmask_b32_e32 v2, v2, v5, vcc
	v_mul_lo_u32 v5, v3, v2
	v_add_u32_e32 v3, v5, v3
	v_cmp_ne_u32_e32 vcc, v4, v3
	s_and_saveexec_b64 s[8:9], vcc
	s_xor_b64 s[8:9], exec, s[8:9]
	s_cbranch_execz .LBB0_602
	s_waitcnt lgkmcnt(0)
	v_mov_b32_e32 v1, 0x24004
	ds_read_b32 v1, v1
	s_add_u32 s14, s68, 0x3400
	s_addc_u32 s15, s69, 0
	s_waitcnt lgkmcnt(0)
	v_mad_u32_u24 v2, v2, v1, v1
	v_mov_b32_e32 v1, 0
	global_load_dword v1, v1, s[14:15] sc1
	s_waitcnt vmcnt(0)
	v_cmp_lt_u32_e32 vcc, v1, v2
	s_and_saveexec_b64 s[10:11], vcc
	s_cbranch_execz .LBB0_601
	s_add_u32 s12, s96, 0xd3a0200
	s_addc_u32 s13, s97, 0
	s_mov_b32 s3, 1
	s_mov_b64 s[16:17], 0
	v_mov_b32_e32 v1, 0
	s_branch .LBB0_592

.LBB0_596:
	global_load_dword v3, v1, s[14:15] sc1
	s_add_i32 s3, s3, 1
	s_mov_b64 s[22:23], -1
	s_waitcnt vmcnt(0)
	v_cmp_ge_u32_e32 vcc, v3, v2
	s_orn2_b64 s[20:21], vcc, exec
	s_branch .LBB0_591

.LBB0_605:
	s_or_b64 exec, exec, s[10:11]
	v_cvt_f32_u32_e32 v4, v1
	s_waitcnt vmcnt(0)
	v_readfirstlane_b32 s3, v3
	s_add_u32 s10, s96, 0xd3a3400
	s_addc_u32 s11, s97, 0
	v_rcp_iflag_f32_e32 v4, v4
	v_add_u32_e32 v2, s3, v2
	v_add_u32_e32 v5, 1, v2
	s_mov_b64 s[12:13], -1
	v_mul_f32_e32 v3, 0x4f7ffffe, v4
	v_cvt_u32_f32_e32 v3, v3
	v_sub_u32_e32 v4, 0, v1
	v_mul_lo_u32 v4, v4, v3
	v_mul_hi_u32 v4, v3, v4
	v_add_u32_e32 v3, v3, v4
	v_mul_hi_u32 v3, v2, v3
	v_mul_lo_u32 v4, v3, v1
	v_sub_u32_e32 v2, v2, v4
	v_add_u32_e32 v6, 1, v3
	v_cmp_ge_u32_e32 vcc, v2, v1
	v_sub_u32_e32 v4, v2, v1
	s_nop 0
	v_cndmask_b32_e32 v3, v3, v6, vcc
	v_cndmask_b32_e32 v2, v2, v4, vcc
	v_add_u32_e32 v4, 1, v3
	v_cmp_ge_u32_e32 vcc, v2, v1
	s_nop 1
	v_cndmask_b32_e32 v4, v3, v4, vcc
	v_mul_lo_u32 v2, v1, v4
	v_add_u32_e32 v1, v2, v1
	v_mov_b32_e32 v4, v1
	v_cmp_ne_u32_e32 vcc, v5, v1
	v_mov_b64_e32 v[2:3], s[10:11]
	s_and_saveexec_b64 s[8:9], vcc
	s_cbranch_execz .LBB0_617
	v_mov_b32_e32 v1, 0
	global_load_dword v2, v1, s[10:11] sc1
	s_mov_b64 s[16:17], 0
	s_waitcnt vmcnt(0)
	v_cmp_lt_u32_e32 vcc, v2, v4
	s_and_saveexec_b64 s[14:15], vcc
	s_cbranch_execz .LBB0_616
	s_add_u32 s12, s96, 0xd3a0200
	s_addc_u32 s13, s97, 0
	s_mov_b32 s3, 1
	s_branch .LBB0_609

.LBB0_613:
	global_load_dword v2, v1, s[10:11] sc1
	s_add_i32 s3, s3, 1
	s_mov_b64 s[20:21], -1
	s_waitcnt vmcnt(0)
	v_cmp_ge_u32_e32 vcc, v2, v4
	s_orn2_b64 s[24:25], vcc, exec
	s_branch .LBB0_608

.LBB0_663:
	s_or_b64 exec, exec, s[12:13]
	v_cvt_f32_u32_e32 v5, v3
	s_waitcnt vmcnt(0)
	v_readfirstlane_b32 s3, v4
	v_sub_u32_e32 v4, 0, v3
	v_rcp_iflag_f32_e32 v5, v5
	v_add_u32_e32 v6, s3, v2
	v_mul_f32_e32 v5, 0x4f7ffffe, v5
	v_cvt_u32_f32_e32 v5, v5
	v_mul_lo_u32 v2, v4, v5
	v_mul_hi_u32 v2, v5, v2
	v_add_u32_e32 v2, v5, v2
	v_mul_hi_u32 v2, v6, v2
	v_mul_lo_u32 v4, v2, v3
	v_sub_u32_e32 v4, v6, v4
	v_add_u32_e32 v5, 1, v2
	v_cmp_ge_u32_e32 vcc, v4, v3
	s_nop 1
	v_cndmask_b32_e32 v2, v2, v5, vcc
	v_sub_u32_e32 v5, v4, v3
	v_cndmask_b32_e32 v4, v4, v5, vcc
	v_add_u32_e32 v5, 1, v2
	v_cmp_ge_u32_e32 vcc, v4, v3
	v_add_u32_e32 v4, 1, v6
	s_nop 0
	v_cndmask_b32_e32 v2, v2, v5, vcc
	v_mul_lo_u32 v5, v3, v2
	v_add_u32_e32 v3, v5, v3
	v_cmp_ne_u32_e32 vcc, v4, v3
	s_and_saveexec_b64 s[10:11], vcc
	s_xor_b64 s[10:11], exec, s[10:11]
	s_cbranch_execz .LBB0_677
	s_waitcnt lgkmcnt(0)
	v_mov_b32_e32 v1, 0x24004
	ds_read_b32 v1, v1
	s_add_u32 s16, s68, 0x3400
	s_addc_u32 s17, s69, 0
	s_waitcnt lgkmcnt(0)
	v_mad_u32_u24 v2, v2, v1, v1
	v_mov_b32_e32 v1, 0
	global_load_dword v1, v1, s[16:17] sc1
	s_waitcnt vmcnt(0)
	v_cmp_lt_u32_e32 vcc, v1, v2
	s_and_saveexec_b64 s[12:13], vcc
	s_cbranch_execz .LBB0_676
	s_add_u32 s14, s96, 0xd3a0200
	s_addc_u32 s15, s97, 0
	s_mov_b32 s3, 1
	s_mov_b64 s[18:19], 0
	v_mov_b32_e32 v1, 0
	s_branch .LBB0_667

.LBB0_671:
	global_load_dword v3, v1, s[16:17] sc1
	s_add_i32 s3, s3, 1
	s_mov_b64 s[24:25], -1
	s_waitcnt vmcnt(0)
	v_cmp_ge_u32_e32 vcc, v3, v2
	s_orn2_b64 s[22:23], vcc, exec
	s_branch .LBB0_666

.LBB0_680:
	s_or_b64 exec, exec, s[12:13]
	v_cvt_f32_u32_e32 v4, v1
	s_waitcnt vmcnt(0)
	v_readfirstlane_b32 s3, v3
	s_add_u32 s12, s96, 0xd3a3400
	s_addc_u32 s13, s97, 0
	v_rcp_iflag_f32_e32 v4, v4
	v_add_u32_e32 v2, s3, v2
	v_add_u32_e32 v5, 1, v2
	s_mov_b64 s[14:15], -1
	v_mul_f32_e32 v3, 0x4f7ffffe, v4
	v_cvt_u32_f32_e32 v3, v3
	v_sub_u32_e32 v4, 0, v1
	v_mul_lo_u32 v4, v4, v3
	v_mul_hi_u32 v4, v3, v4
	v_add_u32_e32 v3, v3, v4
	v_mul_hi_u32 v3, v2, v3
	v_mul_lo_u32 v4, v3, v1
	v_sub_u32_e32 v2, v2, v4
	v_add_u32_e32 v6, 1, v3
	v_cmp_ge_u32_e32 vcc, v2, v1
	v_sub_u32_e32 v4, v2, v1
	s_nop 0
	v_cndmask_b32_e32 v3, v3, v6, vcc
	v_cndmask_b32_e32 v2, v2, v4, vcc
	v_add_u32_e32 v4, 1, v3
	v_cmp_ge_u32_e32 vcc, v2, v1
	s_nop 1
	v_cndmask_b32_e32 v4, v3, v4, vcc
	v_mul_lo_u32 v2, v1, v4
	v_add_u32_e32 v1, v2, v1
	v_mov_b32_e32 v4, v1
	v_cmp_ne_u32_e32 vcc, v5, v1
	v_mov_b64_e32 v[2:3], s[12:13]
	s_and_saveexec_b64 s[10:11], vcc
	s_cbranch_execz .LBB0_692
	v_mov_b32_e32 v1, 0
	global_load_dword v2, v1, s[12:13] sc1
	s_mov_b64 s[18:19], 0
	s_waitcnt vmcnt(0)
	v_cmp_lt_u32_e32 vcc, v2, v4
	s_and_saveexec_b64 s[16:17], vcc
	s_cbranch_execz .LBB0_691
	s_add_u32 s14, s96, 0xd3a0200
	s_addc_u32 s15, s97, 0
	s_mov_b32 s3, 1
	s_branch .LBB0_684

.LBB0_688:
	global_load_dword v2, v1, s[12:13] sc1
	s_add_i32 s3, s3, 1
	s_mov_b64 s[22:23], -1
	s_waitcnt vmcnt(0)
	v_cmp_ge_u32_e32 vcc, v2, v4
	s_orn2_b64 s[26:27], vcc, exec
	s_branch .LBB0_683

.LBB0_842:
	s_or_b64 exec, exec, s[12:13]
	v_cvt_f32_u32_e32 v4, v2
	s_waitcnt vmcnt(0)
	v_readfirstlane_b32 s3, v3
	v_sub_u32_e32 v3, 0, v2
	v_rcp_iflag_f32_e32 v4, v4
	v_add_u32_e32 v5, s3, v1
	v_mul_f32_e32 v4, 0x4f7ffffe, v4
	v_cvt_u32_f32_e32 v4, v4
	v_mul_lo_u32 v1, v3, v4
	v_mul_hi_u32 v1, v4, v1
	v_add_u32_e32 v1, v4, v1
	v_mul_hi_u32 v1, v5, v1
	v_mul_lo_u32 v3, v1, v2
	v_sub_u32_e32 v3, v5, v3
	v_add_u32_e32 v4, 1, v1
	v_cmp_ge_u32_e32 vcc, v3, v2
	s_nop 1
	v_cndmask_b32_e32 v1, v1, v4, vcc
	v_sub_u32_e32 v4, v3, v2
	v_cndmask_b32_e32 v3, v3, v4, vcc
	v_add_u32_e32 v4, 1, v1
	v_cmp_ge_u32_e32 vcc, v3, v2
	v_add_u32_e32 v3, 1, v5
	s_nop 0
	v_cndmask_b32_e32 v1, v1, v4, vcc
	v_mul_lo_u32 v4, v2, v1
	v_add_u32_e32 v2, v4, v2
	v_cmp_ne_u32_e32 vcc, v3, v2
	s_and_saveexec_b64 s[10:11], vcc
	s_xor_b64 s[10:11], exec, s[10:11]
	s_cbranch_execz .LBB0_856
	s_waitcnt lgkmcnt(0)
	v_mov_b32_e32 v0, 0x24004
	ds_read_b32 v0, v0
	s_add_u32 s16, s68, 0x3400
	s_addc_u32 s17, s69, 0
	s_waitcnt lgkmcnt(0)
	v_mad_u32_u24 v1, v1, v0, v0
	v_mov_b32_e32 v0, 0
	global_load_dword v0, v0, s[16:17] sc1
	s_waitcnt vmcnt(0)
	v_cmp_lt_u32_e32 vcc, v0, v1
	s_and_saveexec_b64 s[12:13], vcc
	s_cbranch_execz .LBB0_855
	s_add_u32 s14, s96, 0xd3a0200
	s_addc_u32 s15, s97, 0
	s_mov_b32 s3, 1
	s_mov_b64 s[18:19], 0
	v_mov_b32_e32 v0, 0
	s_branch .LBB0_846

.LBB0_850:
	global_load_dword v2, v0, s[16:17] sc1
	s_add_i32 s3, s3, 1
	s_mov_b64 s[24:25], -1
	s_waitcnt vmcnt(0)
	v_cmp_ge_u32_e32 vcc, v2, v1
	s_orn2_b64 s[22:23], vcc, exec
	s_branch .LBB0_845

.LBB0_859:
	s_or_b64 exec, exec, s[12:13]
	v_cvt_f32_u32_e32 v3, v0
	s_waitcnt vmcnt(0)
	v_readfirstlane_b32 s3, v2
	s_add_u32 s12, s96, 0xd3a3400
	s_addc_u32 s13, s97, 0
	v_rcp_iflag_f32_e32 v3, v3
	v_add_u32_e32 v1, s3, v1
	v_add_u32_e32 v4, 1, v1
	s_mov_b64 s[14:15], -1
	v_mul_f32_e32 v2, 0x4f7ffffe, v3
	v_cvt_u32_f32_e32 v2, v2
	v_sub_u32_e32 v3, 0, v0
	v_mul_lo_u32 v3, v3, v2
	v_mul_hi_u32 v3, v2, v3
	v_add_u32_e32 v2, v2, v3
	v_mul_hi_u32 v2, v1, v2
	v_mul_lo_u32 v3, v2, v0
	v_sub_u32_e32 v1, v1, v3
	v_add_u32_e32 v5, 1, v2
	v_cmp_ge_u32_e32 vcc, v1, v0
	v_sub_u32_e32 v3, v1, v0
	s_nop 0
	v_cndmask_b32_e32 v2, v2, v5, vcc
	v_cndmask_b32_e32 v1, v1, v3, vcc
	v_add_u32_e32 v3, 1, v2
	v_cmp_ge_u32_e32 vcc, v1, v0
	s_nop 1
	v_cndmask_b32_e32 v2, v2, v3, vcc
	v_mul_lo_u32 v1, v0, v2
	v_add_u32_e32 v0, v1, v0
	v_mov_b32_e32 v2, v0
	v_cmp_ne_u32_e32 vcc, v4, v0
	v_mov_b64_e32 v[0:1], s[12:13]
	s_and_saveexec_b64 s[10:11], vcc
	s_cbranch_execz .LBB0_871
	v_mov_b32_e32 v0, 0
	global_load_dword v1, v0, s[12:13] sc1
	s_mov_b64 s[18:19], 0
	s_waitcnt vmcnt(0)
	v_cmp_lt_u32_e32 vcc, v1, v2
	s_and_saveexec_b64 s[16:17], vcc
	s_cbranch_execz .LBB0_870
	s_add_u32 s14, s96, 0xd3a0200
	s_addc_u32 s15, s97, 0
	s_mov_b32 s3, 1
	s_branch .LBB0_863

.LBB0_867:
	global_load_dword v1, v0, s[12:13] sc1
	s_add_i32 s3, s3, 1
	s_mov_b64 s[22:23], -1
	s_waitcnt vmcnt(0)
	v_cmp_ge_u32_e32 vcc, v1, v2
	s_orn2_b64 s[26:27], vcc, exec
	s_branch .LBB0_862
